# speedup vs baseline: 1.0157x; 1.0055x over previous
; #define STAGE_A(b, h, kt) do { const char* _g = (const char*)A + ((size_t)((h) * HALF) * LDA + (size_t)(kt) * BK) * 2; \
;     glds16_s(_g, offA, m0b + SA(b, h)); glds16_s(_g + 64 * LDA * 2, offA, m0b + SA(b, h) + 8192); } while (0)
; #define STAGE_B(b, h, kt) do { const char* _g = (const char*)Bt + ((size_t)((h) * HALF) * LDB + (size_t)(kt) * BK) * 2; \
;     glds16_s(_g, offB, m0b + SB(b, h)); glds16_s(_g + 64 * LDB * 2, offB, m0b + SB(b, h) + 8192); } while (0)
; #define BAR __builtin_amdgcn_s_barrier()
; template <int LDA, int LDB>
; __device__ __forceinline__ void gemm_mainloop(const u16* __restrict__ A, const u16* __restrict__ Bt, const int nt,
;                                               f32x4 (&acc)[2][2][4][2], char* shm, const int tid_in) {
;     ...
;   STAGE_B(0, 0, 0); STAGE_A(0, 0, 0); STAGE_B(0, 1, 0); STAGE_A(0, 1, 0);
;   if (wr == 1) BAR;
.LBB0_185:
	s_ashr_i32 s35, s34, 31
	s_lshl_b64 s[46:47], s[34:35], 20
	s_add_u32 s0, s26, s44
	s_addc_u32 s1, s27, s45
	s_add_u32 s0, s0, s46
	v_mov_b32_e32 v130, v1
	s_addc_u32 s1, s1, s47
	s_ashr_i32 s39, s38, 31
	s_lshl_b64 s[40:41], s[38:39], 20
	s_add_u32 s48, s3, s40
	v_ashrrev_i32_e32 v3, 6, v130
	s_addc_u32 s49, s54, s41
	v_readfirstlane_b32 s16, v3
	s_lshl_b32 s18, s16, 10
	v_lshlrev_b32_e32 v4, 4, v130
	v_and_b32_e32 v5, 32, v130
	v_lshrrev_b32_e32 v6, 3, v130
	s_add_i32 s16, s18, 0
	v_and_b32_e32 v6, 0xffff0, v6
	v_lshrrev_b32_e32 v7, 2, v130
	v_bitop3_b32 v4, v4, v5, 48 bitop3:0x6c
	s_add_i32 s39, s16, 0x10000
	v_and_or_b32 v6, v7, 15, v6
	v_and_or_b32 v4, v130, 64, v4
	s_add_u32 s52, s48, 0x40000
	v_lshl_or_b32 v135, v6, 12, v4
	s_mov_b32 m0, s39
	s_nop 0
	global_load_lds_dwordx4 v135, s[48:49]
	s_addc_u32 s53, s49, 0
	s_add_i32 s88, s16, 0x12000
	s_mov_b32 m0, s88
	s_nop 0
	global_load_lds_dwordx4 v135, s[52:53]
	s_add_u32 s52, s0, 0x40000
	s_mov_b32 m0, s16
	s_nop 0
	global_load_lds_dwordx4 v135, s[0:1]
	s_addc_u32 s53, s1, 0
	s_add_i32 s89, s16, 0x2000
	s_mov_b32 m0, s89
	s_nop 0
	global_load_lds_dwordx4 v135, s[52:53]
	s_add_u32 s52, s48, 0x80000
	s_addc_u32 s53, s49, 0
	s_add_i32 s90, s16, 0x14000
	s_mov_b32 m0, s90
	s_nop 0
	global_load_lds_dwordx4 v135, s[52:53]
	s_add_u32 s52, s48, 0xc0000
	s_addc_u32 s53, s49, 0
	s_add_i32 s91, s16, 0x16000
	s_mov_b32 m0, s91
	s_nop 0
	global_load_lds_dwordx4 v135, s[52:53]
	s_add_u32 s52, s0, 0x80000
	s_addc_u32 s53, s1, 0
	s_add_i32 s92, s16, 0x4000
	s_mov_b32 m0, s92
	s_nop 0
	global_load_lds_dwordx4 v135, s[52:53]
	s_add_u32 s52, s0, 0xc0000
	s_addc_u32 s53, s1, 0
	s_add_i32 s93, s16, 0x6000
	s_mov_b32 m0, s93
	s_nop 0
	global_load_lds_dwordx4 v135, s[52:53]
	v_ashrrev_i32_e32 v2, 8, v130
	v_cmp_eq_u32_e32 vcc, 1, v2
	s_and_saveexec_b64 s[52:53], vcc
	s_cbranch_execz .LBB0_187
	s_barrier

; __device__ __forceinline__ int opq(int x) { asm volatile("" : "+v"(x)); return x; }
; __device__ __forceinline__ void ct_store(const char* shm, u16* __restrict__ dst, const int ldd, const int cl2, const int lcol0) {
;     ...
;   for (int id = opq((int)threadIdx.x); id < n; id += NTHR) {
;     const int row = id >> cl2, c = id & ((1 << cl2) - 1);
;     const u32x4 v = *reinterpret_cast<const u32x4*>(shm + (row * CT_LD + lcol0 + c * 8) * 2);
;     *reinterpret_cast<u32x4*>(dst + (size_t)row * ldd + c * 8) = v;
;   }
.LBB0_214:
	v_ashrrev_i32_e32 v135, 5, v130
	v_and_b32_e32 v134, 0xf8, v132
	v_mad_u64_u32 v[136:137], s[52:53], v135, s70, v[134:135]
	v_lshlrev_b32_e32 v162, 1, v134
	v_lshl_add_u32 v134, v136, 1, 0
	v_ashrrev_i32_e32 v140, 31, v135
	v_mul_lo_u32 v141, s45, v135
	v_mad_u64_u32 v[138:139], s[52:53], s44, v135, 0
	ds_read_b128 v[134:137], v134
	v_mul_lo_u32 v140, s44, v140
	v_add3_u32 v139, v139, v140, v141
	v_add_co_u32_e32 v133, vcc, 1, v133
	v_lshl_add_u64 v[138:139], v[138:139], 1, s[0:1]
	v_add_u32_e32 v130, 0x200, v130
	v_add_u32_e32 v132, 0x1000, v132
	s_or_b64 s[48:49], vcc, s[48:49]
	v_lshl_add_u64 v[138:139], v[138:139], 0, v[162:163]
	s_waitcnt lgkmcnt(0)
	global_store_dwordx4 v[138:139], v[134:137], off sc1
	s_andn2_b64 exec, exec, s[48:49]
	s_cbranch_execnz .LBB0_214
	s_or_b64 exec, exec, s[48:49]

; __device__ __forceinline__ int opq(int x) { asm volatile("" : "+v"(x)); return x; }
; __device__ __forceinline__ void ct_store(const char* shm, u16* __restrict__ dst, const int ldd, const int cl2, const int lcol0) {
;     ...
;   for (int id = opq((int)threadIdx.x); id < n; id += NTHR) {
;     const int row = id >> cl2, c = id & ((1 << cl2) - 1);
;     const u32x4 v = *reinterpret_cast<const u32x4*>(shm + (row * CT_LD + lcol0 + c * 8) * 2);
;     *reinterpret_cast<u32x4*>(dst + (size_t)row * ldd + c * 8) = v;
;   }
.LBB0_218:
	v_ashrrev_i32_e32 v133, 5, v130
	v_and_b32_e32 v132, 0xf8, v131
	v_add_u32_e32 v138, 0x200, v130
	v_add_u32_e32 v139, 0x400, v130
	v_mad_u64_u32 v[134:135], s[48:49], v133, s70, v[132:133]
	v_add_u32_e32 v140, 0x600, v130
	v_ashrrev_i32_e32 v135, 31, v133
	v_mul_lo_u32 v144, s45, v133
	v_mad_u64_u32 v[136:137], s[48:49], s44, v133, 0
	v_ashrrev_i32_e32 v133, 5, v138
	v_ashrrev_i32_e32 v142, 5, v139
	v_ashrrev_i32_e32 v145, 5, v140
	v_mad_u64_u32 v[138:139], s[48:49], v133, s70, v[132:133]
	v_mad_u64_u32 v[140:141], s[48:49], v142, s70, v[132:133]
	v_mul_lo_u32 v146, s44, v135
	v_ashrrev_i32_e32 v139, 31, v133
	v_ashrrev_i32_e32 v141, 31, v142
	v_mul_lo_u32 v156, s45, v142
	v_mad_u64_u32 v[150:151], s[48:49], s44, v142, 0
	v_mad_u64_u32 v[142:143], s[48:49], v145, s70, v[132:133]
	v_lshl_add_u32 v134, v134, 1, 0
	v_mul_lo_u32 v147, s45, v133
	v_mad_u64_u32 v[148:149], s[48:49], s44, v133, 0
	v_ashrrev_i32_e32 v143, 31, v145
	v_mul_lo_u32 v157, s45, v145
	v_mad_u64_u32 v[152:153], s[48:49], s44, v145, 0
	v_add3_u32 v137, v137, v146, v144
	v_lshl_add_u32 v138, v138, 1, 0
	v_mul_lo_u32 v144, s44, v139
	v_lshl_add_u32 v140, v140, 1, 0
	v_mul_lo_u32 v141, s44, v141
	v_lshl_add_u32 v145, v142, 1, 0
	v_lshlrev_b32_e32 v162, 1, v132
	ds_read_b128 v[132:135], v134
	v_mul_lo_u32 v158, s44, v143
	v_lshl_add_u64 v[154:155], v[136:137], 1, s[0:1]
	ds_read_b128 v[136:139], v138
	v_add3_u32 v149, v149, v144, v147
	v_add3_u32 v151, v151, v141, v156
	ds_read_b128 v[140:143], v140
	ds_read_b128 v[144:147], v145
	v_cmp_lt_i32_e32 vcc, s64, v130
	v_add3_u32 v153, v153, v158, v157
	v_add_u32_e32 v131, 0x4000, v131
	v_add_u32_e32 v130, 0x800, v130
	s_or_b64 s[46:47], vcc, s[46:47]
	v_lshl_add_u64 v[154:155], v[154:155], 0, v[162:163]
	v_lshl_add_u64 v[148:149], v[148:149], 1, s[0:1]
	v_lshl_add_u64 v[150:151], v[150:151], 1, s[0:1]
	v_lshl_add_u64 v[152:153], v[152:153], 1, s[0:1]
	v_lshl_add_u64 v[148:149], v[148:149], 0, v[162:163]
	v_lshl_add_u64 v[150:151], v[150:151], 0, v[162:163]
	v_lshl_add_u64 v[152:153], v[152:153], 0, v[162:163]
	s_waitcnt lgkmcnt(3)
	global_store_dwordx4 v[154:155], v[132:135], off sc1
	s_waitcnt lgkmcnt(2)
	global_store_dwordx4 v[148:149], v[136:139], off sc1
	s_waitcnt lgkmcnt(1)
	global_store_dwordx4 v[150:151], v[140:143], off sc1
	s_waitcnt lgkmcnt(0)
	global_store_dwordx4 v[152:153], v[144:147], off sc1
	s_andn2_b64 exec, exec, s[46:47]
	s_cbranch_execnz .LBB0_218

; __device__ __forceinline__ float siluf(float v) { return v * __builtin_amdgcn_rcpf(1.f + __expf(-v)); }
; __device__ __forceinline__ u32x2 pack4(float a, float b, float c, float d) { return u32x2{cvtpk(a, b), cvtpk(c, d)}; }
; __device__ __forceinline__ void phase2(const Params& p, char* shm) {
;     ...
;     if (pn < 16) {
;       char* const cta = shm + ((wr * 64 + fr) * CT_LD + wc * 16 + fq * 4) * 2;
; #pragma unroll
;       for (int ai = 0; ai < 2; ++ai)
; #pragma unroll
;         for (int m = 0; m < 4; ++m) {
;           const f32x4 xa = acc[ai][0][m][0], gb = acc[ai][0][m][1], gc = acc[ai][1][m][0], za = acc[ai][1][m][1];
;           *(u32x2*)(cta + CT_OFF(ai, 0, m, 0)) = pack4(gc[0] * xa[0], gc[1] * xa[1], gc[2] * xa[2], gc[3] * xa[3]);
;           *(u32x2*)(cta + CT_OFF(ai, 0, m, 0) + 128) = pack4(gb[0] * siluf(za[0]), gb[1] * siluf(za[1]), gb[2] * siluf(za[2]), gb[3] * siluf(za[3]));
;         }
.LBB0_220:
	s_and_b64 vcc, exec, s[0:1]
	s_cbranch_vccz .LBB0_180
	v_mul_f32_e32 v122, v122, v126
	v_mul_f32_e32 v126, 0xbfb8aa3b, v118
	v_exp_f32_e32 v126, v126
	v_mul_f32_e32 v123, v123, v127
	v_mul_f32_e32 v124, v124, v128
	v_mul_f32_e32 v125, v125, v129
	s_nop 0
	v_cvt_pk_bf16_f32 v122, v122, v123
	s_nop 0
	v_cvt_pk_bf16_f32 v123, v124, v125
	v_add_f32_e32 v124, 1.0, v126
	v_rcp_f32_e32 v124, v124
	v_mul_f32_e32 v125, 0xbfb8aa3b, v119
	v_exp_f32_e32 v125, v125
	v_lshl_or_b32 v130, v168, 4, v170
	v_add_u32_e32 v130, v130, v169
	v_lshl_add_u32 v130, v130, 1, 0
	v_mul_f32_e32 v118, v118, v124
	ds_write_b64 v130, v[122:123]
	v_mul_f32_e32 v110, v110, v118
	v_add_f32_e32 v118, 1.0, v125
	v_mul_f32_e32 v122, 0xbfb8aa3b, v120
	v_rcp_f32_e32 v118, v118
	v_exp_f32_e32 v122, v122
	v_mul_f32_e32 v123, 0xbfb8aa3b, v121
	v_exp_f32_e32 v123, v123
	v_mul_f32_e32 v118, v119, v118
	v_add_f32_e32 v119, 1.0, v122
	v_rcp_f32_e32 v119, v119
	v_add_f32_e32 v122, 1.0, v123
	v_rcp_f32_e32 v122, v122
	v_mul_f32_e32 v111, v111, v118
	v_mul_f32_e32 v118, v120, v119
	v_mul_f32_e32 v112, v112, v118
	v_mul_f32_e32 v118, v121, v122
	s_nop 0
	v_cvt_pk_bf16_f32 v110, v110, v111
	v_mul_f32_e32 v113, v113, v118
	s_nop 0
	v_cvt_pk_bf16_f32 v111, v112, v113
	ds_write_b64 v130, v[110:111] offset:128
	v_mul_f32_e32 v110, 0xbfb8aa3b, v102
	v_exp_f32_e32 v110, v110
	v_mul_f32_e32 v106, v106, v114
	v_mul_f32_e32 v107, v107, v115
	v_mul_f32_e32 v108, v108, v116
	v_mul_f32_e32 v109, v109, v117
	s_nop 0
	v_cvt_pk_bf16_f32 v106, v106, v107
	s_nop 0
	v_cvt_pk_bf16_f32 v107, v108, v109
	v_add_f32_e32 v108, 1.0, v110
	v_rcp_f32_e32 v108, v108
	v_mul_f32_e32 v109, 0xbfb8aa3b, v103
	v_exp_f32_e32 v109, v109
	ds_write_b64 v130, v[106:107] offset:8448
	v_mul_f32_e32 v102, v102, v108
	v_mul_f32_e32 v94, v94, v102
	v_add_f32_e32 v102, 1.0, v109
	v_mul_f32_e32 v106, 0xbfb8aa3b, v104
	v_rcp_f32_e32 v102, v102
	v_exp_f32_e32 v106, v106
	v_mul_f32_e32 v107, 0xbfb8aa3b, v105
	v_exp_f32_e32 v107, v107
	v_mul_f32_e32 v102, v103, v102
	v_add_f32_e32 v103, 1.0, v106
	v_rcp_f32_e32 v103, v103
	v_add_f32_e32 v106, 1.0, v107
	v_rcp_f32_e32 v106, v106
	v_mul_f32_e32 v95, v95, v102
	v_mul_f32_e32 v102, v104, v103
	v_mul_f32_e32 v96, v96, v102
	v_mul_f32_e32 v102, v105, v106
	s_nop 0
	v_cvt_pk_bf16_f32 v94, v94, v95
	v_mul_f32_e32 v97, v97, v102
	s_nop 0
	v_cvt_pk_bf16_f32 v95, v96, v97
	ds_write_b64 v130, v[94:95] offset:8576
	v_mul_f32_e32 v94, 0xbfb8aa3b, v86
	v_exp_f32_e32 v94, v94
	v_mul_f32_e32 v90, v90, v98
	v_mul_f32_e32 v91, v91, v99
	v_mul_f32_e32 v92, v92, v100
	v_mul_f32_e32 v93, v93, v101
	s_nop 0
	v_cvt_pk_bf16_f32 v90, v90, v91
	s_nop 0
	v_cvt_pk_bf16_f32 v91, v92, v93
	v_add_f32_e32 v92, 1.0, v94
	v_rcp_f32_e32 v92, v92
	v_mul_f32_e32 v93, 0xbfb8aa3b, v87
	v_exp_f32_e32 v93, v93
	ds_write_b64 v130, v[90:91] offset:16896
	v_mul_f32_e32 v86, v86, v92
	v_mul_f32_e32 v74, v74, v86
	v_add_f32_e32 v86, 1.0, v93
	v_mul_f32_e32 v90, 0xbfb8aa3b, v88
	v_rcp_f32_e32 v86, v86
	v_exp_f32_e32 v90, v90
	v_mul_f32_e32 v91, 0xbfb8aa3b, v89
	v_exp_f32_e32 v91, v91
	v_mul_f32_e32 v86, v87, v86
	v_add_f32_e32 v87, 1.0, v90
	v_rcp_f32_e32 v87, v87
	v_add_f32_e32 v90, 1.0, v91
	v_rcp_f32_e32 v90, v90
	v_mul_f32_e32 v75, v75, v86
	v_mul_f32_e32 v86, v88, v87
	v_mul_f32_e32 v76, v76, v86
	v_mul_f32_e32 v86, v89, v90
	s_nop 0
	v_cvt_pk_bf16_f32 v74, v74, v75
	v_mul_f32_e32 v77, v77, v86
	s_nop 0
	v_cvt_pk_bf16_f32 v75, v76, v77
	ds_write_b64 v130, v[74:75] offset:17024
	v_mul_f32_e32 v74, 0xbfb8aa3b, v62
	v_exp_f32_e32 v74, v74
	v_mul_f32_e32 v66, v66, v82
	v_mul_f32_e32 v67, v67, v83
	v_mul_f32_e32 v68, v68, v84
	v_mul_f32_e32 v69, v69, v85
	s_nop 0
	v_cvt_pk_bf16_f32 v66, v66, v67
	s_nop 0
	v_cvt_pk_bf16_f32 v67, v68, v69
	v_add_f32_e32 v68, 1.0, v74
	v_rcp_f32_e32 v68, v68
	v_mul_f32_e32 v69, 0xbfb8aa3b, v63
	v_exp_f32_e32 v69, v69
	ds_write_b64 v130, v[66:67] offset:25344
	v_mul_f32_e32 v62, v62, v68
	v_mul_f32_e32 v50, v50, v62
	v_add_f32_e32 v62, 1.0, v69
	v_mul_f32_e32 v66, 0xbfb8aa3b, v64
	v_rcp_f32_e32 v62, v62
	v_exp_f32_e32 v66, v66
	v_mul_f32_e32 v67, 0xbfb8aa3b, v65
	v_exp_f32_e32 v67, v67
	v_mul_f32_e32 v62, v63, v62
	v_add_f32_e32 v63, 1.0, v66
	v_rcp_f32_e32 v63, v63
	v_add_f32_e32 v66, 1.0, v67
	v_rcp_f32_e32 v66, v66
	v_mul_f32_e32 v51, v51, v62
	v_mul_f32_e32 v62, v64, v63
	v_mul_f32_e32 v52, v52, v62
	v_mul_f32_e32 v62, v65, v66
	v_mul_f32_e32 v53, v53, v62
	v_mul_f32_e32 v62, 0xbfb8aa3b, v58
	v_exp_f32_e32 v62, v62
	s_nop 0
	v_cvt_pk_bf16_f32 v50, v50, v51
	s_nop 0
	v_cvt_pk_bf16_f32 v51, v52, v53
	ds_write_b64 v130, v[50:51] offset:25472
	v_mul_f32_e32 v50, v70, v78
	v_mul_f32_e32 v51, v71, v79
	v_mul_f32_e32 v53, v73, v81
	v_mul_f32_e32 v52, v72, v80
	s_nop 0
	v_cvt_pk_bf16_f32 v50, v50, v51
	s_nop 0
	v_cvt_pk_bf16_f32 v51, v52, v53
	v_add_f32_e32 v53, 1.0, v62
	v_add_u32_e32 v52, 0x10800, v130
	v_rcp_f32_e32 v53, v53
	v_mul_f32_e32 v62, 0xbfb8aa3b, v59
	v_exp_f32_e32 v62, v62
	ds_write_b64 v52, v[50:51]
	v_mul_f32_e32 v51, 0xbfb8aa3b, v60
	v_exp_f32_e32 v51, v51
	v_mul_f32_e32 v52, 0xbfb8aa3b, v61
	v_exp_f32_e32 v52, v52
	v_mul_f32_e32 v50, v58, v53
	v_mul_f32_e32 v46, v46, v50
	v_add_f32_e32 v50, 1.0, v62
	v_rcp_f32_e32 v50, v50
	v_add_f32_e32 v51, 1.0, v51
	v_rcp_f32_e32 v51, v51
	v_add_f32_e32 v52, 1.0, v52
	v_rcp_f32_e32 v52, v52
	v_mul_f32_e32 v50, v59, v50
	v_mul_f32_e32 v47, v47, v50
	v_mul_f32_e32 v50, v60, v51
	v_mul_f32_e32 v48, v48, v50
	v_mul_f32_e32 v50, v61, v52
	v_mul_f32_e32 v49, v49, v50
	s_nop 0
	v_cvt_pk_bf16_f32 v46, v46, v47
	s_nop 0
	v_cvt_pk_bf16_f32 v47, v48, v49
	v_add_u32_e32 v48, 0x10880, v130
	ds_write_b64 v48, v[46:47]
	v_mul_f32_e32 v46, 0xbfb8aa3b, v38
; __device__ __forceinline__ float siluf(float v) { return v * __builtin_amdgcn_rcpf(1.f + __expf(-v)); }
; __device__ __forceinline__ u32x2 pack4(float a, float b, float c, float d) { return u32x2{cvtpk(a, b), cvtpk(c, d)}; }
; __device__ __forceinline__ void phase2(const Params& p, char* shm) {
;     ...
;           const f32x4 xa = acc[ai][0][m][0], gb = acc[ai][0][m][1], gc = acc[ai][1][m][0], za = acc[ai][1][m][1];
;           *(u32x2*)(cta + CT_OFF(ai, 0, m, 0)) = pack4(gc[0] * xa[0], gc[1] * xa[1], gc[2] * xa[2], gc[3] * xa[3]);
;           *(u32x2*)(cta + CT_OFF(ai, 0, m, 0) + 128) = pack4(gb[0] * siluf(za[0]), gb[1] * siluf(za[1]), gb[2] * siluf(za[2]), gb[3] * siluf(za[3]));
;         }
;       __syncthreads();
;       { const int c = tid & 7, ch0 = pn * 64 + c * 8, s0 = brow & 4095;
;         u16* Ain = (u16*)(p.ws + OFF_AIN); u16* Eu = (u16*)(p.ws + OFF_EU); u16* Eg = (u16*)(p.ws + OFF_EG);
;         float w0[8], w1[8], w2[8];
; #pragma unroll
;         for (int q = 0; q < 8; ++q) { w0[q] = p.conv_w[ch0 + q]; w1[q] = p.conv_w[CW + ch0 + q]; w2[q] = p.conv_w[2 * CW + ch0 + q]; }
	v_exp_f32_e32 v46, v46
	v_mul_f32_e32 v42, v42, v54
	v_mul_f32_e32 v43, v43, v55
	v_mul_f32_e32 v45, v45, v57
	v_mul_f32_e32 v44, v44, v56
	s_nop 0
	v_cvt_pk_bf16_f32 v42, v42, v43
	s_nop 0
	v_cvt_pk_bf16_f32 v43, v44, v45
	v_add_f32_e32 v45, 1.0, v46
	v_rcp_f32_e32 v45, v45
	v_mul_f32_e32 v46, 0xbfb8aa3b, v39
	v_exp_f32_e32 v46, v46
	v_add_u32_e32 v44, 0x12900, v130
	v_mul_f32_e32 v38, v38, v45
	ds_write_b64 v44, v[42:43]
	v_mul_f32_e32 v30, v30, v38
	v_add_f32_e32 v38, 1.0, v46
	v_mul_f32_e32 v42, 0xbfb8aa3b, v40
	v_rcp_f32_e32 v38, v38
	v_exp_f32_e32 v42, v42
	v_mul_f32_e32 v43, 0xbfb8aa3b, v41
	v_exp_f32_e32 v43, v43
	v_mul_f32_e32 v38, v39, v38
	v_add_f32_e32 v39, 1.0, v42
	v_rcp_f32_e32 v39, v39
	v_add_f32_e32 v42, 1.0, v43
	v_rcp_f32_e32 v42, v42
	v_mul_f32_e32 v31, v31, v38
	v_mul_f32_e32 v38, v40, v39
	v_mul_f32_e32 v32, v32, v38
	v_mul_f32_e32 v38, v41, v42
	v_mul_f32_e32 v33, v33, v38
	s_nop 0
	v_cvt_pk_bf16_f32 v30, v30, v31
	s_nop 0
	v_cvt_pk_bf16_f32 v31, v32, v33
	v_add_u32_e32 v32, 0x12980, v130
	ds_write_b64 v32, v[30:31]
	v_mul_f32_e32 v30, 0xbfb8aa3b, v22
	v_exp_f32_e32 v30, v30
	v_mul_f32_e32 v26, v26, v34
	v_mul_f32_e32 v27, v27, v35
	v_mul_f32_e32 v29, v29, v37
	v_mul_f32_e32 v28, v28, v36
	s_nop 0
	v_cvt_pk_bf16_f32 v26, v26, v27
	s_nop 0
	v_cvt_pk_bf16_f32 v27, v28, v29
	v_add_f32_e32 v29, 1.0, v30
	v_rcp_f32_e32 v29, v29
	v_mul_f32_e32 v30, 0xbfb8aa3b, v23
	v_exp_f32_e32 v30, v30
	v_add_u32_e32 v28, 0x14a00, v130
	v_mul_f32_e32 v22, v22, v29
	ds_write_b64 v28, v[26:27]
	v_mul_f32_e32 v14, v14, v22
	v_add_f32_e32 v22, 1.0, v30
	v_mul_f32_e32 v26, 0xbfb8aa3b, v24
	v_rcp_f32_e32 v22, v22
	v_exp_f32_e32 v26, v26
	v_mul_f32_e32 v27, 0xbfb8aa3b, v25
	v_exp_f32_e32 v27, v27
	v_mul_f32_e32 v22, v23, v22
	v_add_f32_e32 v23, 1.0, v26
	v_rcp_f32_e32 v23, v23
	v_add_f32_e32 v26, 1.0, v27
	v_rcp_f32_e32 v26, v26
	v_mul_f32_e32 v15, v15, v22
	v_mul_f32_e32 v22, v24, v23
	v_mul_f32_e32 v16, v16, v22
	v_mul_f32_e32 v22, v25, v26
	v_mul_f32_e32 v17, v17, v22
	s_nop 0
	v_cvt_pk_bf16_f32 v14, v14, v15
	s_nop 0
	v_cvt_pk_bf16_f32 v15, v16, v17
	v_add_u32_e32 v16, 0x14a80, v130
	ds_write_b64 v16, v[14:15]
	v_mul_f32_e32 v14, 0xbfb8aa3b, v6
	v_exp_f32_e32 v14, v14
	v_mul_f32_e32 v10, v10, v18
	v_mul_f32_e32 v11, v11, v19
	v_mul_f32_e32 v13, v13, v21
	v_mul_f32_e32 v12, v12, v20
	s_nop 0
	v_cvt_pk_bf16_f32 v10, v10, v11
	s_nop 0
	v_cvt_pk_bf16_f32 v11, v12, v13
	v_add_f32_e32 v13, 1.0, v14
	v_rcp_f32_e32 v13, v13
	v_mul_f32_e32 v14, 0xbfb8aa3b, v7
	v_exp_f32_e32 v14, v14
	v_add_u32_e32 v12, 0x16b00, v130
	v_mul_f32_e32 v6, v6, v13
	ds_write_b64 v12, v[10:11]
	v_mul_f32_e32 v2, v2, v6
	v_add_f32_e32 v6, 1.0, v14
	v_mul_f32_e32 v10, 0xbfb8aa3b, v8
	v_rcp_f32_e32 v6, v6
	v_exp_f32_e32 v10, v10
	v_mul_f32_e32 v11, 0xbfb8aa3b, v9
	v_exp_f32_e32 v11, v11
	v_mul_f32_e32 v6, v7, v6
	v_add_f32_e32 v7, 1.0, v10
	v_rcp_f32_e32 v7, v7
	v_add_f32_e32 v10, 1.0, v11
	v_rcp_f32_e32 v10, v10
	v_mul_f32_e32 v3, v3, v6
	v_mul_f32_e32 v6, v8, v7
	v_mul_f32_e32 v4, v4, v6
	v_mul_f32_e32 v6, v9, v10
	v_mul_f32_e32 v5, v5, v6
	s_nop 0
	v_cvt_pk_bf16_f32 v2, v2, v3
	s_nop 0
	v_cvt_pk_bf16_f32 v3, v4, v5
	v_add_u32_e32 v4, 0x16b80, v130
	ds_write_b64 v4, v[2:3]
	v_lshlrev_b32_e32 v2, 3, v167
	v_and_b32_e32 v49, 56, v2
	v_lshl_or_b32 v44, s38, 6, v49
	v_ashrrev_i32_e32 v45, 31, v44
	v_lshl_add_u64 v[6:7], v[44:45], 2, s[50:51]
	v_add_co_u32_e32 v10, vcc, s65, v6
	s_waitcnt lgkmcnt(0)
	s_barrier
; __device__ __forceinline__ float bflo(unsigned v) { return __uint_as_float(v << 16); }
; __device__ __forceinline__ float bfhi(unsigned v) { return __uint_as_float(v & 0xffff0000u); }
; __device__ __forceinline__ void phase2(const Params& p, char* shm) {
;     ...
;       { const int c = tid & 7, ch0 = pn * 64 + c * 8, s0 = brow & 4095;
;         u16* Ain = (u16*)(p.ws + OFF_AIN); u16* Eu = (u16*)(p.ws + OFF_EU); u16* Eg = (u16*)(p.ws + OFF_EG);
;         float w0[8], w1[8], w2[8];
; #pragma unroll
;         for (int q = 0; q < 8; ++q) { w0[q] = p.conv_w[ch0 + q]; w1[q] = p.conv_w[CW + ch0 + q]; w2[q] = p.conv_w[2 * CW + ch0 + q]; }
; #pragma unroll
;         for (int i = 0; i < 4; ++i) {
;           const int row = (tid >> 3) + i * 64;
;           const u32x4 z = {0u, 0u, 0u, 0u};
;           const u32x4 uc = *reinterpret_cast<const u32x4*>(shm + (row * CT_LD + c * 8) * 2);
;           const u32x4 g  = *reinterpret_cast<const u32x4*>(shm + (row * CT_LD + 64 + c * 8) * 2);
;           const u32x4 up = row > 0   ? *reinterpret_cast<const u32x4*>(shm + ((row - 1) * CT_LD + c * 8) * 2) : z;
;           const u32x4 un = row < 255 ? *reinterpret_cast<const u32x4*>(shm + ((row + 1) * CT_LD + c * 8) * 2) : z;
;           const bool defer = (row == 0 && s0 != 0) || (row == 255 && s0 != SEQ - 256);
;           if (!defer) {
;             u32x4 outv;
; #pragma unroll
;             for (int q = 0; q < 4; ++q) {
;               const float y0 = w0[2 * q] * bflo(up[q]) + w1[2 * q] * bflo(uc[q]) + w2[2 * q] * bflo(un[q]);
;               const float y1 = w0[2 * q + 1] * bfhi(up[q]) + w1[2 * q + 1] * bfhi(uc[q]) + w2[2 * q + 1] * bfhi(un[q]);
;               outv[q] = cvtpk(bflo(g[q]) * y0, bfhi(g[q]) * y1);
;             }
;             *reinterpret_cast<u32x4*>(Ain + (size_t)(brow + row) * CW + ch0) = outv;
	global_load_dwordx4 v[2:5], v[6:7], off offset:16
	global_load_dwordx4 v[14:17], v[6:7], off
	v_lshl_add_u64 v[8:9], v[6:7], 0, s[20:21]
	v_addc_co_u32_e32 v11, vcc, 0, v7, vcc
	v_lshl_add_u64 v[6:7], v[6:7], 0, s[30:31]
	global_load_dwordx4 v[22:25], v[10:11], off offset:-4096
	global_load_dwordx4 v[18:21], v[10:11], off
	s_nop 0
	global_load_dwordx4 v[10:13], v[8:9], off offset:16
	s_nop 0
	global_load_dwordx4 v[6:9], v[6:7], off offset:16
	v_ashrrev_i32_e32 v48, 3, v167
	v_or_b32_e32 v52, 64, v49
	v_mul_lo_u32 v53, v48, s70
	v_add_u32_e32 v26, v53, v49
	v_add_u32_e32 v27, v52, v53
	v_lshl_add_u32 v26, v26, 1, 0
	v_lshl_add_u32 v27, v27, 1, 0
	ds_read_b128 v[30:33], v26
	ds_read_b128 v[26:29], v27
	v_add_u32_e32 v50, 0xfffffef8, v49
	v_mov_b32_e32 v34, 0
	v_cmp_lt_i32_e32 vcc, 0, v48
	v_mov_b32_e32 v38, 0
	v_mov_b32_e32 v39, 0
	v_mov_b32_e32 v40, 0
	v_mov_b32_e32 v41, 0
	s_and_saveexec_b64 s[0:1], vcc
	v_add_u32_e32 v35, v50, v53
	v_lshl_add_u32 v35, v35, 1, 0
	ds_read_b128 v[38:41], v35
	s_or_b64 exec, exec, s[0:1]
	v_add_u32_e32 v51, 0x108, v49
	v_cmp_gt_i32_e32 vcc, s74, v48
	v_mov_b32_e32 v35, 0
	v_mov_b32_e32 v36, 0
	v_mov_b32_e32 v37, 0
	s_and_saveexec_b64 s[0:1], vcc
	v_add_u32_e32 v34, v51, v53
	v_lshl_add_u32 v34, v34, 1, 0
	ds_read_b128 v[34:37], v34
	s_or_b64 exec, exec, s[0:1]
	s_and_b32 s0, s40, 0xf00
	s_cmp_lg_u32 s0, 0
	s_cselect_b64 s[38:39], -1, 0
	s_cmpk_lg_i32 s0, 0xf00
	v_cmp_gt_u32_e32 vcc, 8, v167
	s_cselect_b64 s[42:43], -1, 0
	s_and_b64 s[0:1], vcc, s[38:39]
	v_cmp_eq_u32_e32 vcc, s74, v48
	s_and_b64 s[44:45], vcc, s[42:43]
	v_lshl_add_u64 v[42:43], v[44:45], 1, s[12:13]
	s_nor_b64 s[44:45], s[0:1], s[44:45]
	s_waitcnt vmcnt(0)
	s_and_saveexec_b64 s[0:1], s[44:45]
	s_cbranch_execz .LBB0_227
	s_waitcnt lgkmcnt(0)
	v_lshlrev_b32_e32 v47, 16, v34
	v_lshlrev_b32_e32 v46, 16, v30
	s_waitcnt vmcnt(3)
	v_mov_b32_e32 v54, v22
	s_waitcnt vmcnt(2)
	v_mov_b32_e32 v55, v18
	v_lshlrev_b32_e32 v56, 16, v38
	v_pk_mul_f32 v[46:47], v[54:55], v[46:47]
	v_mov_b32_e32 v54, v23
	v_fma_f32 v46, v14, v56, v46
	v_add_f32_e32 v56, v46, v47
	v_and_b32_e32 v47, 0xffff0000, v34
	v_and_b32_e32 v46, 0xffff0000, v30
	v_mov_b32_e32 v55, v19
	v_and_b32_e32 v38, 0xffff0000, v38
	v_pk_mul_f32 v[46:47], v[54:55], v[46:47]
	v_mov_b32_e32 v54, v24
	v_fma_f32 v34, v15, v38, v46
	v_add_f32_e32 v34, v34, v47
	v_lshlrev_b32_e32 v38, 16, v26
	v_and_b32_e32 v46, 0xffff0000, v26
	v_mul_f32_e32 v38, v56, v38
	v_mul_f32_e32 v34, v34, v46
	v_lshlrev_b32_e32 v47, 16, v35
	v_lshlrev_b32_e32 v46, 16, v31
	v_mov_b32_e32 v55, v20
	s_nop 0
	v_cvt_pk_bf16_f32 v34, v38, v34
	v_lshlrev_b32_e32 v38, 16, v39
	v_pk_mul_f32 v[46:47], v[54:55], v[46:47]
	v_and_b32_e32 v55, 0xffff0000, v39
	v_fma_f32 v38, v16, v38, v46
	v_add_f32_e32 v54, v38, v47
	v_and_b32_e32 v39, 0xffff0000, v35
	v_and_b32_e32 v38, 0xffff0000, v31
	v_mov_b32_e32 v46, v25
	v_mov_b32_e32 v47, v21
	v_pk_mul_f32 v[38:39], v[46:47], v[38:39]
	s_waitcnt vmcnt(1)
	v_mov_b32_e32 v46, v10
	v_fma_f32 v35, v17, v55, v38
	v_add_f32_e32 v35, v35, v39
	v_lshlrev_b32_e32 v38, 16, v27
	v_and_b32_e32 v39, 0xffff0000, v27
	v_mul_f32_e32 v38, v54, v38
	v_mul_f32_e32 v35, v35, v39
	s_nop 0
	v_cvt_pk_bf16_f32 v35, v38, v35
	v_lshlrev_b32_e32 v39, 16, v36
	v_lshlrev_b32_e32 v38, 16, v32
	s_waitcnt vmcnt(0)
	v_mov_b32_e32 v47, v6
	v_lshlrev_b32_e32 v54, 16, v40
	v_pk_mul_f32 v[38:39], v[46:47], v[38:39]
	v_mov_b32_e32 v46, v11
	v_fma_f32 v38, v2, v54, v38
	v_add_f32_e32 v54, v38, v39
	v_and_b32_e32 v39, 0xffff0000, v36
	v_and_b32_e32 v38, 0xffff0000, v32
	v_mov_b32_e32 v47, v7
	v_and_b32_e32 v40, 0xffff0000, v40
	v_pk_mul_f32 v[38:39], v[46:47], v[38:39]
	v_mov_b32_e32 v46, v12
	v_fma_f32 v36, v3, v40, v38
	v_add_f32_e32 v36, v36, v39
	v_lshlrev_b32_e32 v38, 16, v28
	v_and_b32_e32 v39, 0xffff0000, v28
	v_mul_f32_e32 v38, v54, v38
	v_mul_f32_e32 v36, v36, v39
	s_nop 0
	v_cvt_pk_bf16_f32 v36, v38, v36
	v_lshlrev_b32_e32 v39, 16, v37
	v_lshlrev_b32_e32 v38, 16, v33
	v_mov_b32_e32 v47, v8
	v_lshlrev_b32_e32 v40, 16, v41
	v_pk_mul_f32 v[38:39], v[46:47], v[38:39]
	v_and_b32_e32 v47, 0xffff0000, v41
	v_fma_f32 v38, v4, v40, v38
	v_add_f32_e32 v46, v38, v39
	v_and_b32_e32 v39, 0xffff0000, v37
	v_and_b32_e32 v38, 0xffff0000, v33
	v_mov_b32_e32 v40, v13
	v_mov_b32_e32 v41, v9
	v_pk_mul_f32 v[38:39], v[40:41], v[38:39]
	s_nop 0
	v_fma_f32 v37, v5, v47, v38
	v_add_f32_e32 v37, v37, v39
	v_lshlrev_b32_e32 v38, 16, v29
	v_and_b32_e32 v39, 0xffff0000, v29
	v_mul_f32_e32 v38, v46, v38
	v_mul_f32_e32 v37, v37, v39
	s_nop 0
	v_cvt_pk_bf16_f32 v37, v38, v37
	v_add_u32_e32 v38, s40, v48
	v_ashrrev_i32_e32 v39, 31, v38
	v_lshlrev_b64 v[38:39], 11, v[38:39]
	v_lshl_add_u64 v[38:39], v[42:43], 0, v[38:39]
	global_store_dwordx4 v[38:39], v[34:37], off

; #define ACC_ZERO(acc) _Pragma("unroll") for (int a_ = 0; a_ < 2; ++a_) _Pragma("unroll") for (int b_ = 0; b_ < 2; ++b_) \
;   _Pragma("unroll") for (int m_ = 0; m_ < 4; ++m_) _Pragma("unroll") for (int n_ = 0; n_ < 2; ++n_) acc[a_][b_][m_][n_] = f32x4{0.f, 0.f, 0.f, 0.f}
; __device__ __forceinline__ void phase4(const Params& p, char* shm) {
;     ...
;   for (int tile = blockIdx.x; tile < 1024; tile += gridDim.x) {
;     const int r = tile >> 8, l = tile & 255, xcd = l & 7, off = l >> 3;
;     const int pm = r * 32 + xcd * 4 + (off & 3), pn = off >> 2;
;     const size_t brow = (size_t)pm * 256; const int bcol = pn * 256;
;     f32x4 acc[2][2][4][2]; ACC_ZERO(acc);
.LBB0_449:
	s_lshl_b32 s6, s39, 11
	s_and_b32 s62, s6, 0x380000
	s_ashr_i32 s6, s61, 3
	s_and_b32 s17, s6, 0xffffffe0
	s_lshl_b32 s6, s61, 2
	s_and_b32 s6, s6, 28
	s_or_b32 s6, s17, s6
	s_bfe_u32 s18, s61, 0x20003
	s_or_b32 s6, s6, s18
	s_lshl_b32 s8, s61, 3
	s_ashr_i32 s7, s6, 31
	s_and_b32 s16, s41, 28
	s_and_b32 s63, s8, 0x700
	s_lshl_b64 s[8:9], s[6:7], 19
	s_add_u32 s64, s26, s8
	s_addc_u32 s65, s27, s9
	s_lshl_b32 s8, s63, 11
	s_add_u32 s66, s26, s8
	s_addc_u32 s67, s27, 0
	s_lshl_b32 s8, s63, 1
	s_add_u32 s12, s24, s8
	s_addc_u32 s13, s25, 0
	s_lshl_b64 s[8:9], s[6:7], 21
	s_add_u32 s12, s12, s8
	s_addc_u32 s13, s13, s9
	s_add_u32 s14, s12, 0x100000
	s_addc_u32 s15, s13, 0
	s_or_b32 s16, s17, s16
	s_or_b32 s16, s16, s18
	v_mov_b32_e32 v4, v3
	v_mov_b32_e32 v5, v3
	s_ashr_i32 s17, s16, 31
	v_mov_b32_e32 v2, v3
	v_mov_b64_e32 v[8:9], v[4:5]
	v_mov_b64_e32 v[12:13], v[4:5]
	v_mov_b64_e32 v[16:17], v[4:5]
	v_mov_b64_e32 v[20:21], v[4:5]
	v_mov_b64_e32 v[24:25], v[4:5]
	v_mov_b64_e32 v[28:29], v[4:5]
	v_mov_b64_e32 v[32:33], v[4:5]
	v_mov_b64_e32 v[36:37], v[4:5]
	v_mov_b64_e32 v[40:41], v[4:5]
	v_mov_b64_e32 v[44:45], v[4:5]
	v_mov_b64_e32 v[48:49], v[4:5]
	v_mov_b64_e32 v[52:53], v[4:5]
	v_mov_b64_e32 v[56:57], v[4:5]
	v_mov_b64_e32 v[60:61], v[4:5]
	v_mov_b64_e32 v[64:65], v[4:5]
	v_mov_b64_e32 v[68:69], v[4:5]
	v_mov_b64_e32 v[72:73], v[4:5]
	v_mov_b64_e32 v[76:77], v[4:5]
	v_mov_b64_e32 v[80:81], v[4:5]
	v_mov_b64_e32 v[84:85], v[4:5]
	v_mov_b64_e32 v[88:89], v[4:5]
	v_mov_b64_e32 v[92:93], v[4:5]
	v_mov_b64_e32 v[96:97], v[4:5]
	v_mov_b64_e32 v[100:101], v[4:5]
	v_mov_b64_e32 v[104:105], v[4:5]
	v_mov_b64_e32 v[108:109], v[4:5]
	v_mov_b64_e32 v[112:113], v[4:5]
	v_mov_b64_e32 v[116:117], v[4:5]
	v_mov_b64_e32 v[120:121], v[4:5]
	v_mov_b64_e32 v[124:125], v[4:5]
	v_mov_b64_e32 v[128:129], v[4:5]
	v_mov_b64_e32 v[132:133], v[4:5]
	s_lshl_b64 s[16:17], s[16:17], 19
	v_mov_b64_e32 v[6:7], v[2:3]
	v_mov_b64_e32 v[10:11], v[2:3]
	v_mov_b64_e32 v[14:15], v[2:3]
	v_mov_b64_e32 v[18:19], v[2:3]
	v_mov_b64_e32 v[22:23], v[2:3]
	v_mov_b64_e32 v[26:27], v[2:3]
	v_mov_b64_e32 v[30:31], v[2:3]
	v_mov_b64_e32 v[34:35], v[2:3]
	v_mov_b64_e32 v[38:39], v[2:3]
	v_mov_b64_e32 v[42:43], v[2:3]
	v_mov_b64_e32 v[46:47], v[2:3]
	v_mov_b64_e32 v[50:51], v[2:3]
	v_mov_b64_e32 v[54:55], v[2:3]
	v_mov_b64_e32 v[58:59], v[2:3]
	v_mov_b64_e32 v[62:63], v[2:3]
	v_mov_b64_e32 v[66:67], v[2:3]
	v_mov_b64_e32 v[70:71], v[2:3]
	v_mov_b64_e32 v[74:75], v[2:3]
	v_mov_b64_e32 v[78:79], v[2:3]
	v_mov_b64_e32 v[82:83], v[2:3]
	v_mov_b64_e32 v[86:87], v[2:3]
	v_mov_b64_e32 v[90:91], v[2:3]
	v_mov_b64_e32 v[94:95], v[2:3]
	v_mov_b64_e32 v[98:99], v[2:3]
	v_mov_b64_e32 v[102:103], v[2:3]
	v_mov_b64_e32 v[106:107], v[2:3]
	v_mov_b64_e32 v[110:111], v[2:3]
	v_mov_b64_e32 v[114:115], v[2:3]
	v_mov_b64_e32 v[118:119], v[2:3]
	v_mov_b64_e32 v[122:123], v[2:3]
	v_mov_b64_e32 v[126:127], v[2:3]
	v_mov_b64_e32 v[130:131], v[2:3]
	s_mov_b64 s[20:21], -1
	s_branch .LBB0_451

; __device__ __forceinline__ int opq(int x) { asm volatile("" : "+v"(x)); return x; }
; __device__ __forceinline__ void ct_store(const char* shm, u16* __restrict__ dst, const int ldd, const int cl2, const int lcol0) {
;     ...
;   for (int id = opq((int)threadIdx.x); id < n; id += NTHR) {
;     const int row = id >> cl2, c = id & ((1 << cl2) - 1);
;     const u32x4 v = *reinterpret_cast<const u32x4*>(shm + (row * CT_LD + lcol0 + c * 8) * 2);
;     *reinterpret_cast<u32x4*>(dst + (size_t)row * ldd + c * 8) = v;
;   }
.LBB0_462:
	v_ashrrev_i32_e32 v12, 5, v4
	v_and_b32_e32 v2, 0xf8, v6
	v_mad_u64_u32 v[8:9], s[16:17], v12, s55, v[2:3]
	v_lshl_add_u32 v8, v8, 1, 0
	ds_read_b128 v[8:11], v8
	v_ashrrev_i32_e32 v13, 31, v12
	v_lshlrev_b64 v[12:13], 12, v[12:13]
	v_add_co_u32_e32 v7, vcc, 1, v7
	v_lshlrev_b32_e32 v2, 1, v2
	v_lshl_add_u64 v[12:13], s[6:7], 0, v[12:13]
	v_add_u32_e32 v4, 0x200, v4
	v_add_u32_e32 v6, 0x1000, v6
	s_or_b64 s[14:15], vcc, s[14:15]
	v_lshl_add_u64 v[12:13], v[12:13], 0, v[2:3]
	s_waitcnt lgkmcnt(0)
	global_store_dwordx4 v[12:13], v[8:11], off sc1
	s_andn2_b64 exec, exec, s[14:15]
	s_cbranch_execnz .LBB0_462
	s_or_b64 exec, exec, s[14:15]

; __device__ __forceinline__ int opq(int x) { asm volatile("" : "+v"(x)); return x; }
; __device__ __forceinline__ void ct_store(const char* shm, u16* __restrict__ dst, const int ldd, const int cl2, const int lcol0) {
;     ...
;   for (int id = opq((int)threadIdx.x); id < n; id += NTHR) {
;     const int row = id >> cl2, c = id & ((1 << cl2) - 1);
;     const u32x4 v = *reinterpret_cast<const u32x4*>(shm + (row * CT_LD + lcol0 + c * 8) * 2);
;     *reinterpret_cast<u32x4*>(dst + (size_t)row * ldd + c * 8) = v;
;   }
.LBB0_466:
	v_ashrrev_i32_e32 v6, 5, v4
	v_and_b32_e32 v8, 0xf8, v5
	v_add_u32_e32 v9, 0x200, v4
	v_add_u32_e32 v13, 0x400, v4
	v_mad_u64_u32 v[10:11], s[14:15], v6, s55, v[8:9]
	v_add_u32_e32 v15, 0x600, v4
	v_ashrrev_i32_e32 v7, 31, v6
	v_ashrrev_i32_e32 v12, 5, v9
	v_ashrrev_i32_e32 v14, 5, v13
	v_lshl_add_u32 v9, v10, 1, 0
	v_ashrrev_i32_e32 v16, 5, v15
	v_lshlrev_b64 v[10:11], 12, v[6:7]
	v_mad_u64_u32 v[18:19], s[14:15], v12, s55, v[8:9]
	v_ashrrev_i32_e32 v13, 31, v12
	v_mad_u64_u32 v[20:21], s[14:15], v14, s55, v[8:9]
	v_ashrrev_i32_e32 v15, 31, v14
	v_lshlrev_b32_e32 v2, 1, v8
	v_mad_u64_u32 v[22:23], s[14:15], v16, s55, v[8:9]
	v_ashrrev_i32_e32 v17, 31, v16
	v_lshl_add_u64 v[10:11], s[6:7], 0, v[10:11]
	v_lshl_add_u32 v21, v18, 1, 0
	v_lshlrev_b64 v[18:19], 12, v[12:13]
	v_lshl_add_u32 v20, v20, 1, 0
	v_lshlrev_b64 v[14:15], 12, v[14:15]
	ds_read_b128 v[6:9], v9
	v_lshl_add_u32 v30, v22, 1, 0
	v_lshlrev_b64 v[22:23], 12, v[16:17]
	v_lshl_add_u64 v[24:25], v[10:11], 0, v[2:3]
	ds_read_b128 v[10:13], v21
	v_lshl_add_u64 v[26:27], s[6:7], 0, v[18:19]
	v_lshl_add_u64 v[28:29], s[6:7], 0, v[14:15]
	ds_read_b128 v[14:17], v20
	ds_read_b128 v[18:21], v30
	v_cmp_lt_i32_e32 vcc, s57, v4
	v_add_u32_e32 v5, 0x4000, v5
	v_add_u32_e32 v4, 0x800, v4
	s_or_b64 s[12:13], vcc, s[12:13]
	v_lshl_add_u64 v[22:23], s[6:7], 0, v[22:23]
	v_lshl_add_u64 v[26:27], v[26:27], 0, v[2:3]
	v_lshl_add_u64 v[28:29], v[28:29], 0, v[2:3]
	v_lshl_add_u64 v[22:23], v[22:23], 0, v[2:3]
	s_waitcnt lgkmcnt(3)
	global_store_dwordx4 v[24:25], v[6:9], off sc1
	s_waitcnt lgkmcnt(2)
	global_store_dwordx4 v[26:27], v[10:13], off sc1
	s_waitcnt lgkmcnt(1)
	global_store_dwordx4 v[28:29], v[14:17], off sc1
	s_waitcnt lgkmcnt(0)
	global_store_dwordx4 v[22:23], v[18:21], off sc1
	s_andn2_b64 exec, exec, s[12:13]
	s_cbranch_execnz .LBB0_466
	s_branch .LBB0_448

; __device__ __forceinline__ int opq(int x) { asm volatile("" : "+v"(x)); return x; }
; __device__ __forceinline__ void ct_store(const char* shm, u16* __restrict__ dst, const int ldd, const int cl2, const int lcol0) {
;   const int n = 256 << cl2;
; #pragma unroll 4
;   for (int id = opq((int)threadIdx.x); id < n; id += NTHR) {
;     const int row = id >> cl2, c = id & ((1 << cl2) - 1);
;     const u32x4 v = *reinterpret_cast<const u32x4*>(shm + (row * CT_LD + lcol0 + c * 8) * 2);
;     *reinterpret_cast<u32x4*>(dst + (size_t)row * ldd + c * 8) = v;
;   }
; }
.LBB0_519:
	v_ashrrev_i32_e32 v10, 5, v2
	v_and_b32_e32 v6, 0xf8, v4
	v_mad_u64_u32 v[8:9], s[46:47], v10, s41, v[6:7]
	v_lshlrev_b32_e32 v130, 1, v6
	v_lshl_add_u32 v6, v8, 1, 0
	ds_read_b128 v[6:9], v6
	v_ashrrev_i32_e32 v11, 31, v10
	v_lshlrev_b64 v[10:11], 12, v[10:11]
	v_add_co_u32_e32 v5, vcc, 1, v5
	v_lshl_add_u64 v[10:11], s[4:5], 0, v[10:11]
	v_add_u32_e32 v2, 0x200, v2
	v_add_u32_e32 v4, 0x1000, v4
	s_or_b64 s[12:13], vcc, s[12:13]
	v_lshl_add_u64 v[10:11], v[10:11], 0, v[130:131]
	s_waitcnt lgkmcnt(0)
	global_store_dwordx4 v[10:11], v[6:9], off sc1
	s_andn2_b64 exec, exec, s[12:13]
	s_cbranch_execnz .LBB0_519
	s_or_b64 exec, exec, s[12:13]

; __device__ __forceinline__ int opq(int x) { asm volatile("" : "+v"(x)); return x; }
; __device__ __forceinline__ void ct_store(const char* shm, u16* __restrict__ dst, const int ldd, const int cl2, const int lcol0) {
;   const int n = 256 << cl2;
; #pragma unroll 4
;   for (int id = opq((int)threadIdx.x); id < n; id += NTHR) {
;     const int row = id >> cl2, c = id & ((1 << cl2) - 1);
;     const u32x4 v = *reinterpret_cast<const u32x4*>(shm + (row * CT_LD + lcol0 + c * 8) * 2);
;     *reinterpret_cast<u32x4*>(dst + (size_t)row * ldd + c * 8) = v;
;   }
; }
.LBB0_523:
	v_ashrrev_i32_e32 v4, 5, v2
	v_and_b32_e32 v6, 0xf8, v3
	v_add_u32_e32 v7, 0x200, v2
	v_add_u32_e32 v11, 0x400, v2
	v_mad_u64_u32 v[8:9], s[12:13], v4, s41, v[6:7]
	v_add_u32_e32 v13, 0x600, v2
	v_ashrrev_i32_e32 v5, 31, v4
	v_ashrrev_i32_e32 v10, 5, v7
	v_ashrrev_i32_e32 v12, 5, v11
	v_lshl_add_u32 v7, v8, 1, 0
	v_ashrrev_i32_e32 v14, 5, v13
	v_lshlrev_b64 v[8:9], 12, v[4:5]
	v_mad_u64_u32 v[16:17], s[12:13], v10, s41, v[6:7]
	v_ashrrev_i32_e32 v11, 31, v10
	v_mad_u64_u32 v[18:19], s[12:13], v12, s41, v[6:7]
	v_ashrrev_i32_e32 v13, 31, v12
	v_lshlrev_b32_e32 v130, 1, v6
	v_mad_u64_u32 v[20:21], s[12:13], v14, s41, v[6:7]
	v_ashrrev_i32_e32 v15, 31, v14
	v_lshl_add_u64 v[8:9], s[4:5], 0, v[8:9]
	v_lshl_add_u32 v19, v16, 1, 0
	v_lshlrev_b64 v[16:17], 12, v[10:11]
	v_lshl_add_u32 v18, v18, 1, 0
	v_lshlrev_b64 v[12:13], 12, v[12:13]
	ds_read_b128 v[4:7], v7
	v_lshl_add_u32 v28, v20, 1, 0
	v_lshlrev_b64 v[20:21], 12, v[14:15]
	v_lshl_add_u64 v[22:23], v[8:9], 0, v[130:131]
	ds_read_b128 v[8:11], v19
	v_lshl_add_u64 v[24:25], s[4:5], 0, v[16:17]
	v_lshl_add_u64 v[26:27], s[4:5], 0, v[12:13]
	ds_read_b128 v[12:15], v18
	ds_read_b128 v[16:19], v28
	v_cmp_lt_i32_e32 vcc, s44, v2
	v_add_u32_e32 v3, 0x4000, v3
	v_add_u32_e32 v2, 0x800, v2
	s_or_b64 s[8:9], vcc, s[8:9]
	v_lshl_add_u64 v[20:21], s[4:5], 0, v[20:21]
	v_lshl_add_u64 v[24:25], v[24:25], 0, v[130:131]
	v_lshl_add_u64 v[26:27], v[26:27], 0, v[130:131]
	v_lshl_add_u64 v[20:21], v[20:21], 0, v[130:131]
	s_waitcnt lgkmcnt(3)
	global_store_dwordx4 v[22:23], v[4:7], off sc1
	s_waitcnt lgkmcnt(2)
	global_store_dwordx4 v[24:25], v[8:11], off sc1
	s_waitcnt lgkmcnt(1)
	global_store_dwordx4 v[26:27], v[12:15], off sc1
	s_waitcnt lgkmcnt(0)
	global_store_dwordx4 v[20:21], v[16:19], off sc1
	s_andn2_b64 exec, exec, s[8:9]
	s_cbranch_execnz .LBB0_523
	s_branch .LBB0_509
